# compression-bias partial-sum items moved to the last 64 waves (the waves with one fewer weight-conversion item)
# speedup vs baseline: 1.0020x; 1.0020x over previous
; __device__ __forceinline__ void convert_layer(const Ctx& C, int l) {
;     ...
;         float* cb = (float*)(ws + WS_CBP) + (size_t)l * 64 * 256;
;         for (int it = C.gw; it < 64; it += C.NGW) {
;             const int kv = it >> 5, ch = it & 31;
;             const float* pos = kv ? INF(13, l, 2048) : INF(12, l, 2048);
;             const float* w1 = kv ? INF(17, l, 2048 * 256) : INF(14, l, 2048 * 256);
.LBB0_109:
	s_sub_i32 s4, s22, s70
	s_add_i32 s4, s4, 64
	s_cmp_lt_u32 s4, 64
	s_cbranch_scc1 .LBB0_111
	s_lshl_b32 s2, s22, 6
	s_cbranch_execz .LBB0_112
	s_branch .LBB0_116
.LBB0_111:
.LBB0_112:
	v_lshlrev_b32_e32 v4, 2, v67
	v_mov_b32_e32 v5, 0
	v_lshl_add_u64 v[6:7], s[20:21], 0, v[4:5]
	s_mov_b64 s[0:1], 0x3902000
	s_lshl_b32 s2, s22, 6
	v_lshl_add_u64 v[6:7], v[6:7], 0, s[0:1]
	s_lshl_b32 s3, s68, 9
	s_mov_b32 s1, 0
	s_movk_i32 s10, 0x1000
	s_lshl_b32 s11, s4, 6

; __device__ __forceinline__ void convert_layer(const Ctx& C, int l) {
;     ...
;         float* cb = (float*)(ws + WS_CBP) + (size_t)l * 64 * 256;
;         for (int it = C.gw; it < 64; it += C.NGW) {
;             const int kv = it >> 5, ch = it & 31;
;             const float* pos = kv ? INF(13, l, 2048) : INF(12, l, 2048);
;             const float* w1 = kv ? INF(17, l, 2048 * 256) : INF(14, l, 2048 * 256);
.LBB0_1500:
	v_readlane_b32 s72, v253, 48
	v_readlane_b32 s85, v253, 61
	s_sub_i32 s34, s34, s70
	s_add_i32 s34, s34, 64
	s_cmp_gt_u32 s34, 63
	v_readlane_b32 s80, v253, 56
	v_readlane_b32 s81, v253, 57
	v_readlane_b32 s86, v253, 62
	v_readlane_b32 s87, v253, 63
	v_readlane_b32 s10, v254, 27
	v_readlane_b32 s85, v254, 61
	v_readlane_b32 s73, v253, 49
	v_readlane_b32 s74, v253, 50
	v_readlane_b32 s75, v253, 51
	v_readlane_b32 s76, v253, 52
	v_readlane_b32 s77, v253, 53
	v_readlane_b32 s78, v253, 54
	v_readlane_b32 s79, v253, 55
	v_readlane_b32 s82, v253, 58
	v_readlane_b32 s83, v253, 59
	v_readlane_b32 s84, v253, 60
	s_cbranch_scc1 .LBB0_1506
	v_lshlrev_b32_e32 v0, 2, v66
	v_lshl_add_u64 v[2:3], s[4:5], 0, v[0:1]
	s_mov_b64 s[0:1], 0x3912000
	v_lshl_add_u64 v[6:7], v[2:3], 0, s[0:1]
	s_lshl_b32 s2, s34, 6
